# up-proj conv/gate epilogue: n0 packed results kept in regs and stored with n1 as one dwordx4 (permlane16_swap) per row group
# speedup vs baseline: 1.0155x; 1.0026x over previous
; #define LAS __attribute__((address_space(3)))
; #define CG_LOADW(N) do { _Pragma("unroll") for (int bj = 0; bj < 2; ++bj) { const int ch = 128 * u.pn + 32 * wc + 16 * (N) + 4 * fq + bj * DFF; \
;             wq[N][bj][0] = *(const f32x4*)(cw + ch); wq[N][bj][1] = *(const f32x4*)(cw + DUP + ch); wq[N][bj][2] = *(const f32x4*)(cw + 2 * DUP + ch); wq[N][bj][3] = *(const f32x4*)(cbias + ch); } } while (0)
;     __device__ __forceinline__ void operator()(const f32x4 (&acc)[2][2][4][2], const Unit& u, int wr, int wc, int fr, int fq) const {
;         if (wr == 0) { __builtin_amdgcn_s_barrier(); } asm volatile("" ::: "memory");
;         LAS float* X = (LAS float*)xl;
;         f32x4 wq[2][2][4];
;     ...
;         CG_LOADW(0);
; #pragma unroll
;         for (int ai = 0; ai < 2; ++ai) {
;             const int s = 2 * ai + wr;
;             if (fr == 0) {
; #pragma unroll
;                 for (int bj = 0; bj < 2; ++bj)
; #pragma unroll
;                     for (int n = 0; n < 2; ++n) *(LAS f32x4*)(X + ((s * 2 + 0) * 2 + bj) * 128 + 32 * wc + 16 * n + 4 * fq) = acc[ai][bj][0][n];
;             }
;             if (fr == 15) {
; #pragma unroll
;                 for (int bj = 0; bj < 2; ++bj)
; #pragma unroll
;                     for (int n = 0; n < 2; ++n) *(LAS f32x4*)(X + ((s * 2 + 1) * 2 + bj) * 128 + 32 * wc + 16 * n + 4 * fq) = acc[ai][bj][3][n];
;             }
.LBB0_1002:
	v_mbcnt_lo_u32_b32 v128, s9, 0
	v_mbcnt_hi_u32_b32 v180, s9, v128
	s_lshl_b32 s8, s8, 7
	v_lshrrev_b32_e32 v128, 2, v180
	s_or_b32 s46, s8, s76
	v_and_b32_e32 v168, 28, v128
	v_add_u32_e32 v178, s46, v168
	v_ashrrev_i32_e32 v179, 31, v178
	v_lshlrev_b64 v[128:129], 2, v[178:179]
	v_lshl_add_u64 v[130:131], s[20:21], 0, v[128:129]
	v_lshl_add_u64 v[132:133], s[36:37], 0, v[128:129]
	v_lshl_add_u64 v[156:157], s[38:39], 0, v[128:129]
	v_lshl_add_u64 v[158:159], s[22:23], 0, v[128:129]
	v_add_co_u32_e32 v128, vcc, s72, v130
	global_load_dwordx4 v[140:143], v[130:131], off
	global_load_dwordx4 v[148:151], v[132:133], off
	v_addc_co_u32_e32 v129, vcc, 0, v131, vcc
	v_add_co_u32_e32 v130, vcc, s72, v132
	global_load_dwordx4 v[136:139], v[156:157], off
	s_nop 0
	v_addc_co_u32_e32 v131, vcc, 0, v133, vcc
	global_load_dwordx4 v[152:155], v[158:159], off
	global_load_dwordx4 v[132:135], v[128:129], off offset:3072
	global_load_dwordx4 v[144:147], v[130:131], off offset:3072
	v_add_co_u32_e32 v128, vcc, s72, v156
	v_and_b32_e32 v181, 0x70, v180
	s_nop 0
	v_addc_co_u32_e32 v129, vcc, 0, v157, vcc
	v_add_co_u32_e32 v156, vcc, 0x2000, v158
	global_load_dwordx4 v[128:131], v[128:129], off offset:3072
	s_nop 0
	v_addc_co_u32_e32 v157, vcc, 0, v159, vcc
	global_load_dwordx4 v[156:159], v[156:157], off offset:3072
	v_bfe_u32 v246, v180, 5, 1
	v_bfe_u32 v247, v180, 4, 1
	v_lshlrev_b32_e32 v246, 4, v246
	v_lshl_or_b32 v246, v247, 5, v246
	v_lshl_add_u32 v246, s46, 1, v246
	v_mov_b32_e32 v247, 0
	v_and_b32_e32 v180, 15, v180
	v_cmp_lt_i32_e32 vcc, 14, v180
	s_mov_b64 s[8:9], 0
	s_and_saveexec_b64 s[12:13], vcc
	s_xor_b64 s[12:13], exec, s[12:13]
	s_cbranch_execnz .LBB0_1005
	s_or_saveexec_b64 s[12:13], s[12:13]
	v_add_u32_e32 v182, s80, v181
	s_xor_b64 exec, exec, s[12:13]
	s_cbranch_execnz .LBB0_1006

;     __device__ __forceinline__ void operator()(const f32x4 (&acc)[2][2][4][2], const Unit& u, int wr, int wc, int fr, int fq) const {
;     ...
;         asm volatile("s_waitcnt lgkmcnt(0)" ::: "memory");
;         __builtin_amdgcn_s_barrier(); asm volatile("" ::: "memory");
; #pragma unroll
;         for (int n = 0; n < 2; ++n) {
;             const int chg = 128 * u.pn + 32 * wc + 16 * n + 4 * fq;
;             if (n == 1) CG_LOADW(1);
;             f32x4 w0[2], w1[2], w2[2], bb[2], w0m[2], w2m[2];
; #pragma unroll
;             for (int bj = 0; bj < 2; ++bj) {
;                 w0[bj] = wq[n][bj][0]; w1[bj] = wq[n][bj][1]; w2[bj] = wq[n][bj][2]; bb[bj] = wq[n][bj][3];
;                 w0m[bj] = (fr == 0) ? w0[bj] : (f32x4){0.f, 0.f, 0.f, 0.f}; w2m[bj] = (fr == 15) ? w2[bj] : (f32x4){0.f, 0.f, 0.f, 0.f};
;             }
; #pragma unroll
;             for (int ai = 0; ai < 2; ++ai) {
;                 const int s = 2 * ai + wr;
;                 f32x4 xp[2], xn[2];
; #pragma unroll
;                 for (int bj = 0; bj < 2; ++bj) {
;                     xp[bj] = *(const LAS f32x4*)(X + ((((s + 3) & 3) * 2 + 1) * 2 + bj) * 128 + 32 * wc + 16 * n + 4 * fq);
;                     xn[bj] = *(const LAS f32x4*)(X + ((((s + 1) & 3) * 2 + 0) * 2 + bj) * 128 + 32 * wc + 16 * n + 4 * fq);
;                 }
;                 f32x4 cvv[4][2];
; #pragma unroll
;                 for (int bj = 0; bj < 2; ++bj) {
;                     const f32x4 a0 = acc[ai][bj][0][n], a1 = acc[ai][bj][1][n], a2 = acc[ai][bj][2][n], a3 = acc[ai][bj][3][n];
;                     f32x4 c0 = bb[bj] + w1[bj] * a0 + w2[bj] * a1 + w0m[bj] * xp[bj];
;                     f32x4 c1 = bb[bj] + w1[bj] * a1 + w0[bj] * a0 + w2[bj] * a2;
;                     f32x4 c2 = bb[bj] + w1[bj] * a2 + w0[bj] * a1 + w2[bj] * a3;
;                     f32x4 c3 = bb[bj] + w1[bj] * a3 + w0[bj] * a2 + w2m[bj] * xn[bj];
;                     DPP_FMAC4(c0, a3, w0[bj], "row_shr:1");
;                     DPP_FMAC4(c3, a0, w2[bj], "row_shl:1");
;                     cvv[0][bj] = c0; cvv[1][bj] = c1; cvv[2][bj] = c2; cvv[3][bj] = c3;
;                 }
; #pragma unroll
;                 for (int m = 0; m < 4; ++m) {
;                     const int lr = 128 * ai + 64 * wr + 4 * fr + m;
;                     const int R = 254 * u.pm + lr;
;                     const int b = R >= (H2_BSTRIDE + 1) ? 1 : 0;
.LBB0_1014:
	s_or_b64 exec, exec, s[12:13]
	v_lshlrev_b32_e32 v196, 2, v168
	s_waitcnt lgkmcnt(0)
	s_barrier
	v_add_u32_e32 v222, s80, v196
	v_add_u32_e32 v219, s88, v196
	v_cmp_eq_u32_e32 vcc, 0, v180
	v_add_u32_e32 v220, s83, v222
	ds_read_b128 v[196:199], v219 offset:1024
	ds_read_b128 v[200:203], v219 offset:1536
	ds_read_b128 v[208:211], v220
	ds_read_b128 v[226:229], v220 offset:512
	s_waitcnt vmcnt(0)
	v_pk_fma_f32 v[206:207], v[124:125], v[148:149], v[152:153]
	v_cndmask_b32_e32 v195, 0, v141, vcc
	v_cndmask_b32_e32 v194, 0, v140, vcc
	v_pk_fma_f32 v[206:207], v[116:117], v[136:137], v[206:207]
	v_cmp_eq_u32_e64 s[8:9], 15, v180
	v_pk_fma_f32 v[204:205], v[126:127], v[150:151], v[154:155]
	s_waitcnt lgkmcnt(0)
	v_pk_fma_f32 v[206:207], v[194:195], v[196:197], v[206:207]
	v_pk_fma_f32 v[196:197], v[110:111], v[150:151], v[154:155]
	v_cndmask_b32_e32 v193, 0, v143, vcc
	v_cndmask_b32_e32 v192, 0, v142, vcc
	v_cndmask_b32_e64 v189, 0, v139, s[8:9]
	v_cndmask_b32_e64 v188, 0, v138, s[8:9]
	v_pk_fma_f32 v[204:205], v[118:119], v[138:139], v[204:205]
	v_pk_fma_f32 v[196:197], v[114:115], v[142:143], v[196:197]
	v_pk_fma_f32 v[204:205], v[192:193], v[198:199], v[204:205]
	v_pk_fma_f32 v[198:199], v[108:109], v[148:149], v[152:153]
	v_pk_fma_f32 v[196:197], v[188:189], v[210:211], v[196:197]
	v_pk_fma_f32 v[210:211], v[120:121], v[144:145], v[156:157]
	v_cndmask_b32_e64 v191, 0, v137, s[8:9]
	v_cndmask_b32_e64 v190, 0, v136, s[8:9]
	v_cndmask_b32_e32 v187, 0, v133, vcc
	v_cndmask_b32_e32 v186, 0, v132, vcc
	v_pk_fma_f32 v[198:199], v[112:113], v[140:141], v[198:199]
	v_pk_fma_f32 v[210:211], v[104:105], v[128:129], v[210:211]
	v_pk_fma_f32 v[198:199], v[190:191], v[208:209], v[198:199]
	v_pk_fma_f32 v[208:209], v[122:123], v[146:147], v[158:159]
	v_pk_fma_f32 v[210:211], v[186:187], v[200:201], v[210:211]
	v_pk_fma_f32 v[200:201], v[98:99], v[146:147], v[158:159]
	v_lshl_or_b32 v221, v180, 2, s75
	v_cndmask_b32_e32 v185, 0, v135, vcc
	v_cndmask_b32_e32 v184, 0, v134, vcc
	v_cndmask_b32_e64 v181, 0, v131, s[8:9]
	v_cndmask_b32_e64 v180, 0, v130, s[8:9]
	v_pk_fma_f32 v[208:209], v[106:107], v[130:131], v[208:209]
	v_pk_fma_f32 v[200:201], v[102:103], v[134:135], v[200:201]
	s_mul_i32 s41, s47, 0xfe
	v_pk_fma_f32 v[208:209], v[184:185], v[202:203], v[208:209]
	v_pk_fma_f32 v[202:203], v[96:97], v[144:145], v[156:157]
	v_pk_fma_f32 v[200:201], v[180:181], v[228:229], v[200:201]
	v_cndmask_b32_e64 v183, 0, v129, s[8:9]
	v_cndmask_b32_e64 v182, 0, v128, s[8:9]
	v_mov_b32_e32 v223, v196
	v_pk_fma_f32 v[202:203], v[100:101], v[132:133], v[202:203]
	v_mov_b32_e32 v196, v209
	v_mov_b32_e32 v209, v201
	v_add_u32_e32 v201, s41, v221
	v_pk_fma_f32 v[202:203], v[182:183], v[226:227], v[202:203]
	v_cmp_lt_i32_e64 s[12:13], s93, v201
	v_mov_b32_e32 v224, v198
	v_mov_b32_e32 v198, v210
	v_mov_b32_e32 v210, v203
	v_cndmask_b32_e64 v203, 0, v217, s[12:13]
	v_add_u32_e32 v201, v201, v203
	v_mov_b32_e32 v212, v204
	v_add_u32_e32 v204, -1, v201
	v_add_u32_e32 v201, -1, v221
	v_cmp_gt_u32_e64 s[14:15], s92, v201
	v_cmp_gt_u32_e64 s[16:17], s74, v204
	v_mov_b32_e32 v225, v206
	s_and_b64 s[48:49], s[14:15], s[16:17]
	v_cndmask_b32_e64 v206, 0, v218, s[12:13]
	s_nop 1
	v_fmac_f32_dpp v225, v108, v140 row_shr:1 row_mask:0xf bank_mask:0xf bound_ctrl:1
	v_fmac_f32_dpp v207, v109, v141 row_shr:1 row_mask:0xf bank_mask:0xf bound_ctrl:1
	v_fmac_f32_dpp v212, v110, v142 row_shr:1 row_mask:0xf bank_mask:0xf bound_ctrl:1
	v_fmac_f32_dpp v205, v111, v143 row_shr:1 row_mask:0xf bank_mask:0xf bound_ctrl:1
	s_nop 1
	v_fmac_f32_dpp v224, v124, v136 row_shl:1 row_mask:0xf bank_mask:0xf bound_ctrl:1
	v_fmac_f32_dpp v199, v125, v137 row_shl:1 row_mask:0xf bank_mask:0xf bound_ctrl:1
	v_fmac_f32_dpp v223, v126, v138 row_shl:1 row_mask:0xf bank_mask:0xf bound_ctrl:1
	v_fmac_f32_dpp v197, v127, v139 row_shl:1 row_mask:0xf bank_mask:0xf bound_ctrl:1
	s_nop 1
	v_fmac_f32_dpp v198, v96, v132 row_shr:1 row_mask:0xf bank_mask:0xf bound_ctrl:1
	v_fmac_f32_dpp v211, v97, v133 row_shr:1 row_mask:0xf bank_mask:0xf bound_ctrl:1
	v_fmac_f32_dpp v208, v98, v134 row_shr:1 row_mask:0xf bank_mask:0xf bound_ctrl:1
	v_fmac_f32_dpp v196, v99, v135 row_shr:1 row_mask:0xf bank_mask:0xf bound_ctrl:1
	s_nop 1
	v_fmac_f32_dpp v202, v120, v128 row_shl:1 row_mask:0xf bank_mask:0xf bound_ctrl:1
	v_fmac_f32_dpp v210, v121, v129 row_shl:1 row_mask:0xf bank_mask:0xf bound_ctrl:1
	v_fmac_f32_dpp v200, v122, v130 row_shl:1 row_mask:0xf bank_mask:0xf bound_ctrl:1
	v_fmac_f32_dpp v209, v123, v131 row_shl:1 row_mask:0xf bank_mask:0xf bound_ctrl:1
	s_and_saveexec_b64 s[12:13], s[48:49]
	s_cbranch_execz .LBB0_1016
	v_mul_f32_e32 v201, 0xbfb8aa3b, v225
	v_mul_f32_e32 v203, 0xbfb8aa3b, v207
	v_exp_f32_e32 v201, v201
	v_exp_f32_e32 v203, v203
	v_mul_f32_e32 v226, 0xbfb8aa3b, v212
	v_mov_b32_e32 v229, v169
	v_add_f32_e32 v201, 1.0, v201
	v_add_f32_e32 v203, 1.0, v203
	v_rcp_f32_e32 v201, v201
	v_rcp_f32_e32 v203, v203
	v_mul_f32_e32 v201, v225, v201
	v_mul_f32_e32 v203, v207, v203
	v_mul_f32_e32 v207, 0xbfb8aa3b, v205
	v_mul_f32_e32 v198, v198, v201
	v_exp_f32_e32 v201, v226
	v_exp_f32_e32 v207, v207
	v_mul_f32_e32 v203, v211, v203
	v_cvt_pk_bf16_f32 v230, v198, v203
	v_add_f32_e32 v201, 1.0, v201
	v_add_f32_e32 v207, 1.0, v207
	v_rcp_f32_e32 v201, v201
	v_rcp_f32_e32 v207, v207
	v_mul_f32_e32 v198, v212, v201
	v_mul_f32_e32 v201, v205, v207
	v_mul_f32_e32 v196, v196, v201
	v_mul_f32_e32 v198, v208, v198
	v_cvt_pk_bf16_f32 v231, v198, v196
	v_or_b32_e32 v196, v204, v206
	v_mul_lo_u32 v228, v196, s94
	v_lshl_add_u64 v[228:229], s[28:29], 0, v[228:229]
	v_lshl_add_u64 v[228:229], v[178:179], 1, v[228:229]
; #define LAS __attribute__((address_space(3)))
; __device__ __forceinline__ float silu_(float x) { return x * fast_sigmoid(x); }
;     __device__ __forceinline__ void operator()(const f32x4 (&acc)[2][2][4][2], const Unit& u, int wr, int wc, int fr, int fq) const {
;     ...
; #pragma unroll
;             for (int ai = 0; ai < 2; ++ai) {
;                 const int s = 2 * ai + wr;
;                 f32x4 xp[2], xn[2];
; #pragma unroll
;                 for (int bj = 0; bj < 2; ++bj) {
;                     xp[bj] = *(const LAS f32x4*)(X + ((((s + 3) & 3) * 2 + 1) * 2 + bj) * 128 + 32 * wc + 16 * n + 4 * fq);
;                     xn[bj] = *(const LAS f32x4*)(X + ((((s + 1) & 3) * 2 + 0) * 2 + bj) * 128 + 32 * wc + 16 * n + 4 * fq);
;                 }
;                 f32x4 cvv[4][2];
; #pragma unroll
;                 for (int bj = 0; bj < 2; ++bj) {
;                     const f32x4 a0 = acc[ai][bj][0][n], a1 = acc[ai][bj][1][n], a2 = acc[ai][bj][2][n], a3 = acc[ai][bj][3][n];
;                     f32x4 c0 = bb[bj] + w1[bj] * a0 + w2[bj] * a1 + w0m[bj] * xp[bj];
;                     f32x4 c1 = bb[bj] + w1[bj] * a1 + w0[bj] * a0 + w2[bj] * a2;
;                     f32x4 c2 = bb[bj] + w1[bj] * a2 + w0[bj] * a1 + w2[bj] * a3;
;                     f32x4 c3 = bb[bj] + w1[bj] * a3 + w0[bj] * a2 + w2m[bj] * xn[bj];
;                     DPP_FMAC4(c0, a3, w0[bj], "row_shr:1");
;                     DPP_FMAC4(c3, a0, w2[bj], "row_shl:1");
;                     cvv[0][bj] = c0; cvv[1][bj] = c1; cvv[2][bj] = c2; cvv[3][bj] = c3;
;                 }
; #pragma unroll
;                 for (int m = 0; m < 4; ++m) {
;                     const int lr = 128 * ai + 64 * wr + 4 * fr + m;
;                     const int R = 254 * u.pm + lr;
;                     const int b = R >= (H2_BSTRIDE + 1) ? 1 : 0;
;                     const int t = R - 1 - H2_BSTRIDE * b;
;                     const bool valid = lr >= 1 && lr <= 254 && t >= 0 && t < S;
;                     if (valid) {
;                         u32x2 w;
;                         w.x = pk2(silu_(cvv[m][0][0]) * cvv[m][1][0], silu_(cvv[m][0][1]) * cvv[m][1][1]);
;                         w.y = pk2(silu_(cvv[m][0][2]) * cvv[m][1][2], silu_(cvv[m][0][3]) * cvv[m][1][3]);
;                         *(u32x2*)(act + (size_t)(b * S + t) * DFF + chg) = w;
;                     }
;                 }
.LBB0_1016:
	s_or_b64 exec, exec, s[12:13]
	v_add3_u32 v196, s41, v221, 1
	v_cmp_lt_i32_e64 s[12:13], s93, v196
	v_cmp_gt_u32_e64 s[14:15], s92, v221
	s_nop 0
	v_cndmask_b32_e64 v198, 0, v217, s[12:13]
	v_add_u32_e32 v196, v196, v198
	v_add_u32_e32 v196, -1, v196
	v_cmp_gt_u32_e64 s[16:17], s74, v196
	s_and_b64 s[50:51], s[14:15], s[16:17]
	v_cndmask_b32_e64 v198, 0, v218, s[12:13]
	s_and_saveexec_b64 s[12:13], s[50:51]
	s_cbranch_execz .LBB0_1018
	v_pk_fma_f32 v[228:229], v[116:117], v[148:149], v[152:153]
	v_pk_fma_f32 v[226:227], v[118:119], v[150:151], v[154:155]
	v_pk_fma_f32 v[124:125], v[124:125], v[140:141], v[228:229]
	v_pk_fma_f32 v[228:229], v[104:105], v[144:145], v[156:157]
	v_pk_fma_f32 v[124:125], v[112:113], v[136:137], v[124:125]
	v_pk_fma_f32 v[126:127], v[126:127], v[142:143], v[226:227]
	v_mul_f32_e32 v201, 0xbfb8aa3b, v124
	v_exp_f32_e32 v201, v201
	v_mul_f32_e32 v203, 0xbfb8aa3b, v125
	v_exp_f32_e32 v203, v203
	v_pk_fma_f32 v[120:121], v[120:121], v[132:133], v[228:229]
	v_add_f32_e32 v201, 1.0, v201
	v_rcp_f32_e32 v201, v201
	v_add_f32_e32 v203, 1.0, v203
	v_rcp_f32_e32 v203, v203
	v_pk_fma_f32 v[126:127], v[114:115], v[138:139], v[126:127]
	v_pk_fma_f32 v[120:121], v[100:101], v[128:129], v[120:121]
	v_mul_f32_e32 v124, v124, v201
	v_mul_f32_e32 v120, v120, v124
	v_mul_f32_e32 v124, v125, v203
	v_mul_f32_e32 v125, 0xbfb8aa3b, v126
	v_exp_f32_e32 v125, v125
	v_mul_f32_e32 v201, 0xbfb8aa3b, v127
	v_exp_f32_e32 v201, v201
	v_mul_f32_e32 v121, v121, v124
	v_add_f32_e32 v124, 1.0, v125
	v_rcp_f32_e32 v124, v124
	v_add_f32_e32 v125, 1.0, v201
	v_rcp_f32_e32 v125, v125
	v_pk_fma_f32 v[226:227], v[106:107], v[146:147], v[158:159]
	v_cvt_pk_bf16_f32 v232, v120, v121
	v_mul_f32_e32 v121, v126, v124
	v_pk_fma_f32 v[122:123], v[122:123], v[134:135], v[226:227]
	s_nop 0
	v_pk_fma_f32 v[122:123], v[102:103], v[130:131], v[122:123]
	s_nop 0
	v_mul_f32_e32 v121, v122, v121
	v_mul_f32_e32 v122, v127, v125
	v_mul_f32_e32 v122, v123, v122
	v_cvt_pk_bf16_f32 v233, v121, v122
	v_or_b32_e32 v122, v196, v198
	v_mul_lo_u32 v122, v122, s94
	v_mov_b32_e32 v123, v169
	v_lshl_add_u64 v[122:123], s[28:29], 0, v[122:123]
	v_lshl_add_u64 v[122:123], v[178:179], 1, v[122:123]
.LBB0_1018:
	s_or_b64 exec, exec, s[12:13]
	v_or_b32_e32 v120, 2, v221
	v_add_u32_e32 v121, s41, v120
	v_cmp_lt_i32_e64 s[12:13], s93, v121
	v_cmp_gt_u32_e64 s[14:15], s95, v120
	s_nop 0
	v_cndmask_b32_e64 v122, 0, v217, s[12:13]
	v_add_u32_e32 v121, v121, v122
	v_add_u32_e32 v201, -1, v121
	v_cmp_gt_u32_e64 s[16:17], s74, v201
	s_and_b64 s[52:53], s[14:15], s[16:17]
	v_cndmask_b32_e64 v203, 0, v218, s[12:13]
	s_and_saveexec_b64 s[12:13], s[52:53]
	s_cbranch_execz .LBB0_1020
	v_pk_fma_f32 v[112:113], v[112:113], v[148:149], v[152:153]
	v_pk_fma_f32 v[100:101], v[100:101], v[144:145], v[156:157]
	v_pk_fma_f32 v[112:113], v[116:117], v[140:141], v[112:113]
	v_pk_fma_f32 v[100:101], v[104:105], v[132:133], v[100:101]
	v_pk_fma_f32 v[108:109], v[108:109], v[136:137], v[112:113]
	v_pk_fma_f32 v[102:103], v[102:103], v[146:147], v[158:159]
	v_mul_f32_e32 v104, 0xbfb8aa3b, v108
	v_exp_f32_e32 v104, v104
	v_mul_f32_e32 v105, 0xbfb8aa3b, v109
	v_pk_fma_f32 v[102:103], v[106:107], v[134:135], v[102:103]
	v_exp_f32_e32 v105, v105
	v_pk_fma_f32 v[98:99], v[98:99], v[130:131], v[102:103]
	v_add_f32_e32 v102, 1.0, v104
	v_pk_fma_f32 v[114:115], v[114:115], v[150:151], v[154:155]
	v_rcp_f32_e32 v102, v102
	v_pk_fma_f32 v[114:115], v[118:119], v[142:143], v[114:115]
	v_add_f32_e32 v103, 1.0, v105
	v_pk_fma_f32 v[110:111], v[110:111], v[138:139], v[114:115]
	v_rcp_f32_e32 v103, v103
	v_pk_fma_f32 v[96:97], v[96:97], v[128:129], v[100:101]
	v_mul_f32_e32 v101, 0xbfb8aa3b, v110
	v_mul_f32_e32 v100, v108, v102
	v_exp_f32_e32 v101, v101
	v_mul_f32_e32 v102, 0xbfb8aa3b, v111
	v_exp_f32_e32 v102, v102
	v_mul_f32_e32 v96, v96, v100
	v_mul_f32_e32 v100, v109, v103
	v_mul_f32_e32 v97, v97, v100
	v_add_f32_e32 v100, 1.0, v101
	v_rcp_f32_e32 v100, v100
	v_add_f32_e32 v101, 1.0, v102
	v_rcp_f32_e32 v101, v101
	v_cvt_pk_bf16_f32 v234, v96, v97
	v_mul_f32_e32 v97, v110, v100
	v_mul_f32_e32 v97, v98, v97
	v_mul_f32_e32 v98, v111, v101
	v_mul_f32_e32 v98, v99, v98
	v_cvt_pk_bf16_f32 v235, v97, v98
	v_or_b32_e32 v98, v201, v203
	v_mul_lo_u32 v98, v98, s94
	v_mov_b32_e32 v99, v169
	v_lshl_add_u64 v[98:99], s[28:29], 0, v[98:99]
	v_lshl_add_u64 v[98:99], v[178:179], 1, v[98:99]
.LBB0_1020:
	s_or_b64 exec, exec, s[12:13]
	v_or_b32_e32 v96, 3, v221
	v_add_u32_e32 v97, s41, v96
	v_cmp_lt_i32_e64 s[12:13], s93, v97
	v_cmp_gt_u32_e64 s[14:15], s95, v96
	s_nop 0
	v_cndmask_b32_e64 v98, 0, v217, s[12:13]
	v_add_u32_e32 v97, v97, v98
	v_add_u32_e32 v205, -1, v97
	v_cmp_gt_u32_e64 s[16:17], s74, v205
	s_and_b64 s[54:55], s[14:15], s[16:17]
	v_cndmask_b32_e64 v207, 0, v218, s[12:13]
	s_and_saveexec_b64 s[12:13], s[54:55]
	s_cbranch_execz .LBB0_1022
	v_mul_f32_e32 v96, 0xbfb8aa3b, v224
	v_mul_f32_e32 v97, 0xbfb8aa3b, v199
	v_exp_f32_e32 v96, v96
	v_exp_f32_e32 v97, v97
	v_mul_f32_e32 v98, 0xbfb8aa3b, v223
	v_mul_f32_e32 v99, 0xbfb8aa3b, v197
	v_exp_f32_e32 v98, v98
	v_exp_f32_e32 v99, v99
	v_add_f32_e32 v96, 1.0, v96
	v_add_f32_e32 v97, 1.0, v97
	v_rcp_f32_e32 v96, v96
	v_rcp_f32_e32 v97, v97
	v_add_f32_e32 v98, 1.0, v98
	v_add_f32_e32 v99, 1.0, v99
	v_rcp_f32_e32 v98, v98
	v_rcp_f32_e32 v99, v99
	v_mul_f32_e32 v96, v224, v96
	v_mul_f32_e32 v97, v199, v97
	v_mul_f32_e32 v96, v202, v96
	v_mul_f32_e32 v97, v210, v97
	v_cvt_pk_bf16_f32 v236, v96, v97
	v_mul_f32_e32 v97, v223, v98
	v_mul_f32_e32 v98, v197, v99
	v_mul_f32_e32 v97, v200, v97
	v_mul_f32_e32 v98, v209, v98
	v_cvt_pk_bf16_f32 v237, v97, v98
	v_or_b32_e32 v98, v205, v207
	v_mul_lo_u32 v98, v98, s94
	v_mov_b32_e32 v99, v169
	v_lshl_add_u64 v[98:99], s[28:29], 0, v[98:99]
	v_lshl_add_u64 v[98:99], v[178:179], 1, v[98:99]
; #define LAS __attribute__((address_space(3)))
; __device__ __forceinline__ float silu_(float x) { return x * fast_sigmoid(x); }
;     __device__ __forceinline__ void operator()(const f32x4 (&acc)[2][2][4][2], const Unit& u, int wr, int wc, int fr, int fq) const {
;     ...
; #pragma unroll
;             for (int ai = 0; ai < 2; ++ai) {
;                 const int s = 2 * ai + wr;
;                 f32x4 xp[2], xn[2];
; #pragma unroll
;                 for (int bj = 0; bj < 2; ++bj) {
;                     xp[bj] = *(const LAS f32x4*)(X + ((((s + 3) & 3) * 2 + 1) * 2 + bj) * 128 + 32 * wc + 16 * n + 4 * fq);
;                     xn[bj] = *(const LAS f32x4*)(X + ((((s + 1) & 3) * 2 + 0) * 2 + bj) * 128 + 32 * wc + 16 * n + 4 * fq);
;                 }
;                 f32x4 cvv[4][2];
; #pragma unroll
;                 for (int bj = 0; bj < 2; ++bj) {
;                     const f32x4 a0 = acc[ai][bj][0][n], a1 = acc[ai][bj][1][n], a2 = acc[ai][bj][2][n], a3 = acc[ai][bj][3][n];
;                     f32x4 c0 = bb[bj] + w1[bj] * a0 + w2[bj] * a1 + w0m[bj] * xp[bj];
;                     f32x4 c1 = bb[bj] + w1[bj] * a1 + w0[bj] * a0 + w2[bj] * a2;
;                     f32x4 c2 = bb[bj] + w1[bj] * a2 + w0[bj] * a1 + w2[bj] * a3;
;                     f32x4 c3 = bb[bj] + w1[bj] * a3 + w0[bj] * a2 + w2m[bj] * xn[bj];
;                     DPP_FMAC4(c0, a3, w0[bj], "row_shr:1");
;                     DPP_FMAC4(c3, a0, w2[bj], "row_shl:1");
;                     cvv[0][bj] = c0; cvv[1][bj] = c1; cvv[2][bj] = c2; cvv[3][bj] = c3;
;                 }
; #pragma unroll
;                 for (int m = 0; m < 4; ++m) {
;                     const int lr = 128 * ai + 64 * wr + 4 * fr + m;
;                     const int R = 254 * u.pm + lr;
;                     const int b = R >= (H2_BSTRIDE + 1) ? 1 : 0;
;                     const int t = R - 1 - H2_BSTRIDE * b;
;                     const bool valid = lr >= 1 && lr <= 254 && t >= 0 && t < S;
;                     if (valid) {
;                         u32x2 w;
;                         w.x = pk2(silu_(cvv[m][0][0]) * cvv[m][1][0], silu_(cvv[m][0][1]) * cvv[m][1][1]);
;                         w.y = pk2(silu_(cvv[m][0][2]) * cvv[m][1][2], silu_(cvv[m][0][3]) * cvv[m][1][3]);
;                         *(u32x2*)(act + (size_t)(b * S + t) * DFF + chg) = w;
;                     }
;                 }
.LBB0_1022:
	s_or_b64 exec, exec, s[12:13]
	v_lshl_add_u32 v197, v168, 2, s89
	v_add_u32_e32 v199, s82, v222
	ds_read_b128 v[96:99], v197 offset:1024
	ds_read_b128 v[100:103], v197 offset:1536
	ds_read_b128 v[108:111], v199
	ds_read_b128 v[112:115], v199 offset:512
	v_pk_fma_f32 v[104:105], v[94:95], v[150:151], v[154:155]
	v_pk_fma_f32 v[106:107], v[92:93], v[148:149], v[152:153]
	v_pk_fma_f32 v[104:105], v[86:87], v[138:139], v[104:105]
	v_pk_fma_f32 v[106:107], v[84:85], v[136:137], v[106:107]
	s_waitcnt lgkmcnt(3)
	v_pk_fma_f32 v[104:105], v[192:193], v[98:99], v[104:105]
	v_pk_fma_f32 v[98:99], v[76:77], v[148:149], v[152:153]
	v_pk_fma_f32 v[106:107], v[194:195], v[96:97], v[106:107]
	v_pk_fma_f32 v[96:97], v[78:79], v[150:151], v[154:155]
	v_pk_fma_f32 v[98:99], v[80:81], v[140:141], v[98:99]
	v_pk_fma_f32 v[96:97], v[82:83], v[142:143], v[96:97]
	s_waitcnt lgkmcnt(1)
	v_pk_fma_f32 v[98:99], v[190:191], v[108:109], v[98:99]
	v_pk_fma_f32 v[108:109], v[90:91], v[146:147], v[158:159]
	v_pk_fma_f32 v[96:97], v[188:189], v[110:111], v[96:97]
	v_pk_fma_f32 v[110:111], v[88:89], v[144:145], v[156:157]
	v_pk_fma_f32 v[108:109], v[74:75], v[130:131], v[108:109]
	v_pk_fma_f32 v[110:111], v[72:73], v[128:129], v[110:111]
	v_pk_fma_f32 v[108:109], v[184:185], v[102:103], v[108:109]
	v_pk_fma_f32 v[102:103], v[64:65], v[144:145], v[156:157]
	v_pk_fma_f32 v[110:111], v[186:187], v[100:101], v[110:111]
	v_pk_fma_f32 v[102:103], v[68:69], v[132:133], v[102:103]
	v_pk_fma_f32 v[100:101], v[66:67], v[146:147], v[158:159]
	s_waitcnt lgkmcnt(0)
	v_pk_fma_f32 v[102:103], v[182:183], v[112:113], v[102:103]
	v_mov_b32_e32 v112, v110
	v_mov_b32_e32 v110, v108
	v_add_u32_e32 v108, 0x80, v221
	v_add_u32_e32 v113, s41, v108
	v_pk_fma_f32 v[100:101], v[70:71], v[134:135], v[100:101]
	v_cmp_lt_i32_e64 s[12:13], s93, v113
	v_pk_fma_f32 v[100:101], v[180:181], v[114:115], v[100:101]
	s_nop 1
	v_fmac_f32_dpp v106, v76, v140 row_shr:1 row_mask:0xf bank_mask:0xf bound_ctrl:1
	v_fmac_f32_dpp v107, v77, v141 row_shr:1 row_mask:0xf bank_mask:0xf bound_ctrl:1
	v_fmac_f32_dpp v104, v78, v142 row_shr:1 row_mask:0xf bank_mask:0xf bound_ctrl:1
	v_fmac_f32_dpp v105, v79, v143 row_shr:1 row_mask:0xf bank_mask:0xf bound_ctrl:1
	s_nop 1
	v_fmac_f32_dpp v98, v92, v136 row_shl:1 row_mask:0xf bank_mask:0xf bound_ctrl:1
	v_fmac_f32_dpp v99, v93, v137 row_shl:1 row_mask:0xf bank_mask:0xf bound_ctrl:1
	v_fmac_f32_dpp v96, v94, v138 row_shl:1 row_mask:0xf bank_mask:0xf bound_ctrl:1
	v_fmac_f32_dpp v97, v95, v139 row_shl:1 row_mask:0xf bank_mask:0xf bound_ctrl:1
	s_nop 1
	v_fmac_f32_dpp v112, v64, v132 row_shr:1 row_mask:0xf bank_mask:0xf bound_ctrl:1
	v_fmac_f32_dpp v111, v65, v133 row_shr:1 row_mask:0xf bank_mask:0xf bound_ctrl:1
	v_fmac_f32_dpp v110, v66, v134 row_shr:1 row_mask:0xf bank_mask:0xf bound_ctrl:1
	v_fmac_f32_dpp v109, v67, v135 row_shr:1 row_mask:0xf bank_mask:0xf bound_ctrl:1
	s_nop 0
	v_cndmask_b32_e64 v114, 0, v217, s[12:13]
	v_add_u32_e32 v113, v113, v114
	v_add_u32_e32 v184, -1, v113
	v_add_u32_e32 v113, 0x7f, v221
	v_cmp_gt_u32_e64 s[14:15], s92, v113
	v_cmp_gt_u32_e64 s[16:17], s74, v184
	s_and_b64 s[56:57], s[14:15], s[16:17]
	v_cndmask_b32_e64 v185, 0, v218, s[12:13]
	s_nop 1
	v_fmac_f32_dpp v102, v88, v128 row_shl:1 row_mask:0xf bank_mask:0xf bound_ctrl:1
	v_fmac_f32_dpp v103, v89, v129 row_shl:1 row_mask:0xf bank_mask:0xf bound_ctrl:1
	v_fmac_f32_dpp v100, v90, v130 row_shl:1 row_mask:0xf bank_mask:0xf bound_ctrl:1
	v_fmac_f32_dpp v101, v91, v131 row_shl:1 row_mask:0xf bank_mask:0xf bound_ctrl:1
	s_and_saveexec_b64 s[12:13], s[56:57]
	s_cbranch_execz .LBB0_1024
	v_mul_f32_e32 v113, 0xbfb8aa3b, v106
	v_exp_f32_e32 v113, v113
	v_mul_f32_e32 v114, 0xbfb8aa3b, v107
	v_exp_f32_e32 v114, v114
	v_mul_f32_e32 v115, 0xbfb8aa3b, v104
	v_add_f32_e32 v113, 1.0, v113
	v_rcp_f32_e32 v113, v113
	v_add_f32_e32 v114, 1.0, v114
	v_rcp_f32_e32 v114, v114
	v_mul_f32_e32 v106, v106, v113
	v_mul_f32_e32 v106, v112, v106
	v_exp_f32_e32 v112, v115
	v_mul_f32_e32 v113, 0xbfb8aa3b, v105
	v_exp_f32_e32 v113, v113
	v_mul_f32_e32 v107, v107, v114
	v_mul_f32_e32 v107, v111, v107
	v_add_f32_e32 v111, 1.0, v112
	v_rcp_f32_e32 v111, v111
	v_add_f32_e32 v112, 1.0, v113
	v_rcp_f32_e32 v112, v112
	v_cvt_pk_bf16_f32 v238, v106, v107
	v_mul_f32_e32 v104, v104, v111
	v_mul_f32_e32 v104, v110, v104
	v_mul_f32_e32 v105, v105, v112
	v_mul_f32_e32 v105, v109, v105
	v_cvt_pk_bf16_f32 v239, v104, v105
	v_or_b32_e32 v104, v184, v185
	v_mul_lo_u32 v104, v104, s94
	v_mov_b32_e32 v105, v169
	v_lshl_add_u64 v[104:105], s[28:29], 0, v[104:105]
	v_lshl_add_u64 v[104:105], v[178:179], 1, v[104:105]
; __device__ __forceinline__ unsigned pk2(float lo, float hi) { unsigned r; asm("v_cvt_pk_bf16_f32 %0, %1, %2" : "=v"(r) : "v"(lo), "v"(hi)); return r; }
; __device__ __forceinline__ float silu_(float x) { return x * fast_sigmoid(x); }
;     __device__ __forceinline__ void operator()(const f32x4 (&acc)[2][2][4][2], const Unit& u, int wr, int wc, int fr, int fq) const {
;     ...
; #pragma unroll
;                 for (int m = 0; m < 4; ++m) {
;                     const int lr = 128 * ai + 64 * wr + 4 * fr + m;
;                     const int R = 254 * u.pm + lr;
;                     const int b = R >= (H2_BSTRIDE + 1) ? 1 : 0;
;                     const int t = R - 1 - H2_BSTRIDE * b;
;                     const bool valid = lr >= 1 && lr <= 254 && t >= 0 && t < S;
;                     if (valid) {
;                         u32x2 w;
;                         w.x = pk2(silu_(cvv[m][0][0]) * cvv[m][1][0], silu_(cvv[m][0][1]) * cvv[m][1][1]);
;                         w.y = pk2(silu_(cvv[m][0][2]) * cvv[m][1][2], silu_(cvv[m][0][3]) * cvv[m][1][3]);
;                         *(u32x2*)(act + (size_t)(b * S + t) * DFF + chg) = w;
;                     }
;                 }
.LBB0_1024:
	s_or_b64 exec, exec, s[12:13]
	s_add_i32 s12, s41, 0x81
	v_add_u32_e32 v104, s12, v221
	v_cmp_lt_i32_e64 s[12:13], s93, v104
	v_cmp_gt_u32_e64 s[14:15], s92, v108
	s_nop 0
	v_cndmask_b32_e64 v105, 0, v217, s[12:13]
	v_add_u32_e32 v104, v104, v105
	v_add_u32_e32 v180, -1, v104
	v_cmp_gt_u32_e64 s[16:17], s74, v180
	s_and_b64 s[58:59], s[14:15], s[16:17]
	v_cndmask_b32_e64 v181, 0, v218, s[12:13]
	s_and_saveexec_b64 s[12:13], s[58:59]
	s_cbranch_execz .LBB0_1026
	v_pk_fma_f32 v[106:107], v[84:85], v[148:149], v[152:153]
	v_pk_fma_f32 v[104:105], v[86:87], v[150:151], v[154:155]
	v_pk_fma_f32 v[92:93], v[92:93], v[140:141], v[106:107]
	v_pk_fma_f32 v[94:95], v[94:95], v[142:143], v[104:105]
	v_pk_fma_f32 v[92:93], v[80:81], v[136:137], v[92:93]
	v_pk_fma_f32 v[104:105], v[74:75], v[146:147], v[158:159]
	v_pk_fma_f32 v[106:107], v[72:73], v[144:145], v[156:157]
	v_pk_fma_f32 v[90:91], v[90:91], v[134:135], v[104:105]
	v_mul_f32_e32 v104, 0xbfb8aa3b, v92
	v_exp_f32_e32 v104, v104
	v_mul_f32_e32 v105, 0xbfb8aa3b, v93
	v_exp_f32_e32 v105, v105
	v_pk_fma_f32 v[88:89], v[88:89], v[132:133], v[106:107]
	v_add_f32_e32 v104, 1.0, v104
	v_rcp_f32_e32 v104, v104
	v_add_f32_e32 v105, 1.0, v105
	v_rcp_f32_e32 v105, v105
	v_pk_fma_f32 v[94:95], v[82:83], v[138:139], v[94:95]
	v_pk_fma_f32 v[88:89], v[68:69], v[128:129], v[88:89]
	v_mul_f32_e32 v92, v92, v104
	v_mul_f32_e32 v88, v88, v92
	v_mul_f32_e32 v92, v93, v105
	v_mul_f32_e32 v93, 0xbfb8aa3b, v94
	v_exp_f32_e32 v93, v93
	v_mul_f32_e32 v104, 0xbfb8aa3b, v95
	v_exp_f32_e32 v104, v104
	v_mul_f32_e32 v89, v89, v92
	v_add_f32_e32 v92, 1.0, v93
	v_rcp_f32_e32 v92, v92
	v_add_f32_e32 v93, 1.0, v104
	v_rcp_f32_e32 v93, v93
	v_pk_fma_f32 v[90:91], v[70:71], v[130:131], v[90:91]
	v_cvt_pk_bf16_f32 v240, v88, v89
	v_mul_f32_e32 v89, v94, v92
	v_mul_f32_e32 v89, v90, v89
	v_mul_f32_e32 v90, v95, v93
	v_mul_f32_e32 v90, v91, v90
	v_cvt_pk_bf16_f32 v241, v89, v90
	v_or_b32_e32 v90, v180, v181
	v_mul_lo_u32 v90, v90, s94
	v_mov_b32_e32 v91, v169
	v_lshl_add_u64 v[90:91], s[28:29], 0, v[90:91]
	v_lshl_add_u64 v[90:91], v[178:179], 1, v[90:91]
.LBB0_1026:
	s_or_b64 exec, exec, s[12:13]
	v_add_u32_e32 v88, 0x82, v221
	v_add_u32_e32 v89, s41, v88
	v_cmp_lt_i32_e64 s[12:13], s93, v89
	v_cmp_gt_u32_e64 s[14:15], s95, v88
	s_nop 0
	v_cndmask_b32_e64 v90, 0, v217, s[12:13]
	v_add_u32_e32 v89, v89, v90
	v_add_u32_e32 v182, -1, v89
	v_cmp_gt_u32_e64 s[16:17], s74, v182
	s_and_b64 s[60:61], s[14:15], s[16:17]
	v_cndmask_b32_e64 v183, 0, v218, s[12:13]
	s_and_saveexec_b64 s[12:13], s[60:61]
	s_cbranch_execz .LBB0_1028
	v_pk_fma_f32 v[80:81], v[80:81], v[148:149], v[152:153]
	v_pk_fma_f32 v[68:69], v[68:69], v[144:145], v[156:157]
	v_pk_fma_f32 v[80:81], v[84:85], v[140:141], v[80:81]
	v_pk_fma_f32 v[68:69], v[72:73], v[132:133], v[68:69]
	v_pk_fma_f32 v[76:77], v[76:77], v[136:137], v[80:81]
	v_pk_fma_f32 v[70:71], v[70:71], v[146:147], v[158:159]
	v_mul_f32_e32 v72, 0xbfb8aa3b, v76
	v_exp_f32_e32 v72, v72
	v_mul_f32_e32 v73, 0xbfb8aa3b, v77
	v_pk_fma_f32 v[70:71], v[74:75], v[134:135], v[70:71]
	v_exp_f32_e32 v73, v73
	v_pk_fma_f32 v[66:67], v[66:67], v[130:131], v[70:71]
	v_add_f32_e32 v70, 1.0, v72
	v_pk_fma_f32 v[82:83], v[82:83], v[150:151], v[154:155]
	v_rcp_f32_e32 v70, v70
	v_pk_fma_f32 v[82:83], v[86:87], v[142:143], v[82:83]
	v_add_f32_e32 v71, 1.0, v73
	v_pk_fma_f32 v[78:79], v[78:79], v[138:139], v[82:83]
	v_rcp_f32_e32 v71, v71
	v_pk_fma_f32 v[64:65], v[64:65], v[128:129], v[68:69]
	v_mul_f32_e32 v69, 0xbfb8aa3b, v78
	v_mul_f32_e32 v68, v76, v70
	v_exp_f32_e32 v69, v69
	v_mul_f32_e32 v70, 0xbfb8aa3b, v79
	v_exp_f32_e32 v70, v70
	v_mul_f32_e32 v64, v64, v68
	v_mul_f32_e32 v68, v77, v71
	v_mul_f32_e32 v65, v65, v68
	v_add_f32_e32 v68, 1.0, v69
	v_rcp_f32_e32 v68, v68
	v_add_f32_e32 v69, 1.0, v70
	v_rcp_f32_e32 v69, v69
	v_cvt_pk_bf16_f32 v242, v64, v65
	v_mul_f32_e32 v65, v78, v68
	v_mul_f32_e32 v65, v66, v65
	v_mul_f32_e32 v66, v79, v69
	v_mul_f32_e32 v66, v67, v66
	v_cvt_pk_bf16_f32 v243, v65, v66
	v_or_b32_e32 v66, v182, v183
	v_mul_lo_u32 v66, v66, s94
	v_mov_b32_e32 v67, v169
	v_lshl_add_u64 v[66:67], s[28:29], 0, v[66:67]
	v_lshl_add_u64 v[66:67], v[178:179], 1, v[66:67]
.LBB0_1028:
	s_or_b64 exec, exec, s[12:13]
	v_add_u32_e32 v64, 0x83, v221
	v_add_u32_e32 v65, s41, v64
	v_cmp_lt_i32_e64 s[12:13], s93, v65
	v_cmp_gt_u32_e64 s[14:15], s95, v64
	s_nop 0
	v_cndmask_b32_e64 v66, 0, v217, s[12:13]
	v_add_u32_e32 v65, v65, v66
	v_add_u32_e32 v128, -1, v65
	v_cmp_gt_u32_e64 s[16:17], s74, v128
	s_and_b64 s[14:15], s[14:15], s[16:17]
	v_cndmask_b32_e64 v129, 0, v218, s[12:13]
	s_and_saveexec_b64 s[12:13], s[14:15]
	s_cbranch_execz .LBB0_1030
	v_mul_f32_e32 v64, 0xbfb8aa3b, v98
	v_mul_f32_e32 v65, 0xbfb8aa3b, v99
	v_exp_f32_e32 v64, v64
	v_exp_f32_e32 v65, v65
	v_mul_f32_e32 v66, 0xbfb8aa3b, v96
	v_mul_f32_e32 v67, 0xbfb8aa3b, v97
	v_exp_f32_e32 v66, v66
	v_exp_f32_e32 v67, v67
	v_add_f32_e32 v64, 1.0, v64
	v_add_f32_e32 v65, 1.0, v65
	v_rcp_f32_e32 v64, v64
	v_rcp_f32_e32 v65, v65
	v_add_f32_e32 v66, 1.0, v66
	v_add_f32_e32 v67, 1.0, v67
	v_rcp_f32_e32 v66, v66
	v_rcp_f32_e32 v67, v67
	v_mul_f32_e32 v64, v98, v64
	v_mul_f32_e32 v65, v99, v65
	v_mul_f32_e32 v64, v102, v64
	v_mul_f32_e32 v65, v103, v65
	v_cvt_pk_bf16_f32 v244, v64, v65
	v_mul_f32_e32 v65, v96, v66
	v_mul_f32_e32 v66, v97, v67
	v_mul_f32_e32 v65, v100, v65
	v_mul_f32_e32 v66, v101, v66
	v_cvt_pk_bf16_f32 v245, v65, v66
	v_or_b32_e32 v66, v128, v129
	v_mul_lo_u32 v66, v66, s94
	v_mov_b32_e32 v67, v169
	v_lshl_add_u64 v[66:67], s[28:29], 0, v[66:67]
	v_lshl_add_u64 v[66:67], v[178:179], 1, v[66:67]

; __device__ __forceinline__ unsigned pk2(float lo, float hi) { unsigned r; asm("v_cvt_pk_bf16_f32 %0, %1, %2" : "=v"(r) : "v"(lo), "v"(hi)); return r; }
; __device__ __forceinline__ float silu_(float x) { return x * fast_sigmoid(x); }
;     __device__ __forceinline__ void operator()(const f32x4 (&acc)[2][2][4][2], const Unit& u, int wr, int wc, int fr, int fq) const {
;     ...
; #pragma unroll
;                 for (int m = 0; m < 4; ++m) {
;                     const int lr = 128 * ai + 64 * wr + 4 * fr + m;
;                     const int R = 254 * u.pm + lr;
;                     const int b = R >= (H2_BSTRIDE + 1) ? 1 : 0;
;                     const int t = R - 1 - H2_BSTRIDE * b;
;                     const bool valid = lr >= 1 && lr <= 254 && t >= 0 && t < S;
;                     if (valid) {
;                         u32x2 w;
;                         w.x = pk2(silu_(cvv[m][0][0]) * cvv[m][1][0], silu_(cvv[m][0][1]) * cvv[m][1][1]);
;                         w.y = pk2(silu_(cvv[m][0][2]) * cvv[m][1][2], silu_(cvv[m][0][3]) * cvv[m][1][3]);
;                         *(u32x2*)(act + (size_t)(b * S + t) * DFF + chg) = w;
;                     }
;                 }
.LBB0_1034:
	v_mul_f32_e32 v32, 0xbfb8aa3b, v114
	v_mul_f32_e32 v33, 0xbfb8aa3b, v115
	v_exp_f32_e32 v32, v32
	v_exp_f32_e32 v33, v33
	v_mul_f32_e32 v34, 0xbfb8aa3b, v112
	v_mul_f32_e32 v35, 0xbfb8aa3b, v113
	v_exp_f32_e32 v34, v34
	v_exp_f32_e32 v35, v35
	v_add_f32_e32 v32, 1.0, v32
	v_add_f32_e32 v33, 1.0, v33
	v_rcp_f32_e32 v32, v32
	v_rcp_f32_e32 v33, v33
	v_add_f32_e32 v34, 1.0, v34
	v_add_f32_e32 v35, 1.0, v35
	v_rcp_f32_e32 v34, v34
	v_rcp_f32_e32 v35, v35
	v_mul_f32_e32 v32, v114, v32
	v_mul_f32_e32 v33, v115, v33
	v_mul_f32_e32 v32, v118, v32
	v_mul_f32_e32 v33, v119, v33
	v_cvt_pk_bf16_f32 v250, v32, v33
	v_mul_f32_e32 v33, v112, v34
	v_mul_f32_e32 v34, v113, v35
	v_mul_f32_e32 v33, v116, v33
	v_mul_f32_e32 v34, v117, v34
	v_cvt_pk_bf16_f32 v251, v33, v34
	v_or_b32_e32 v34, v205, v207
	v_mul_lo_u32 v168, v34, s94
	v_lshl_add_u64 v[34:35], s[28:29], 0, v[168:169]
	v_lshl_add_u64 v[34:35], v[246:247], 0, v[34:35]
	v_mov_b32_e32 v248, v236
	v_mov_b32_e32 v249, v237
	s_nop 1
	v_permlane16_swap_b32_e32 v248, v250
	v_permlane16_swap_b32_e32 v249, v251
	global_store_dwordx4 v[34:35], v[248:251], off

; __device__ __forceinline__ unsigned pk2(float lo, float hi) { unsigned r; asm("v_cvt_pk_bf16_f32 %0, %1, %2" : "=v"(r) : "v"(lo), "v"(hi)); return r; }
; __device__ __forceinline__ float silu_(float x) { return x * fast_sigmoid(x); }
;     __device__ __forceinline__ void operator()(const f32x4 (&acc)[2][2][4][2], const Unit& u, int wr, int wc, int fr, int fq) const {
;     ...
; #pragma unroll
;                 for (int m = 0; m < 4; ++m) {
;                     const int lr = 128 * ai + 64 * wr + 4 * fr + m;
;                     const int R = 254 * u.pm + lr;
;                     const int b = R >= (H2_BSTRIDE + 1) ? 1 : 0;
;                     const int t = R - 1 - H2_BSTRIDE * b;
;                     const bool valid = lr >= 1 && lr <= 254 && t >= 0 && t < S;
;                     if (valid) {
;                         u32x2 w;
;                         w.x = pk2(silu_(cvv[m][0][0]) * cvv[m][1][0], silu_(cvv[m][0][1]) * cvv[m][1][1]);
;                         w.y = pk2(silu_(cvv[m][0][2]) * cvv[m][1][2], silu_(cvv[m][0][3]) * cvv[m][1][3]);
;                         *(u32x2*)(act + (size_t)(b * S + t) * DFF + chg) = w;
;                     }
;                 }
.LBB0_1039:
	v_mul_f32_e32 v0, 0xbfb8aa3b, v34
	v_mul_f32_e32 v1, 0xbfb8aa3b, v35
	v_exp_f32_e32 v0, v0
	v_exp_f32_e32 v1, v1
	v_mul_f32_e32 v2, 0xbfb8aa3b, v32
	v_mul_f32_e32 v3, 0xbfb8aa3b, v33
	v_exp_f32_e32 v2, v2
	v_exp_f32_e32 v3, v3
	v_add_f32_e32 v0, 1.0, v0
	v_add_f32_e32 v1, 1.0, v1
	v_rcp_f32_e32 v0, v0
	v_rcp_f32_e32 v1, v1
	v_add_f32_e32 v2, 1.0, v2
	v_add_f32_e32 v3, 1.0, v3
	v_rcp_f32_e32 v2, v2
	v_rcp_f32_e32 v3, v3
	v_mul_f32_e32 v0, v34, v0
	v_mul_f32_e32 v1, v35, v1
	v_mul_f32_e32 v0, v38, v0
	v_mul_f32_e32 v1, v39, v1
	v_cvt_pk_bf16_f32 v254, v0, v1
	v_mul_f32_e32 v1, v32, v2
	v_mul_f32_e32 v2, v33, v3
	v_mul_f32_e32 v1, v36, v1
	v_mul_f32_e32 v2, v37, v2
	v_cvt_pk_bf16_f32 v255, v1, v2
	v_or_b32_e32 v2, v128, v129
	v_mul_lo_u32 v168, v2, s94
	v_lshl_add_u64 v[2:3], s[28:29], 0, v[168:169]
	v_lshl_add_u64 v[2:3], v[246:247], 0, v[2:3]
	v_mov_b32_e32 v252, v244
	v_mov_b32_e32 v253, v245
	s_nop 1
	v_permlane16_swap_b32_e32 v252, v254
	v_permlane16_swap_b32_e32 v253, v255
	global_store_dwordx4 v[2:3], v[252:255], off

; __device__ __forceinline__ unsigned pk2(float lo, float hi) { unsigned r; asm("v_cvt_pk_bf16_f32 %0, %1, %2" : "=v"(r) : "v"(lo), "v"(hi)); return r; }
; __device__ __forceinline__ float silu_(float x) { return x * fast_sigmoid(x); }
;     __device__ __forceinline__ void operator()(const f32x4 (&acc)[2][2][4][2], const Unit& u, int wr, int wc, int fr, int fq) const {
;     ...
; #pragma unroll
;                 for (int m = 0; m < 4; ++m) {
;                     const int lr = 128 * ai + 64 * wr + 4 * fr + m;
;                     const int R = 254 * u.pm + lr;
;                     const int b = R >= (H2_BSTRIDE + 1) ? 1 : 0;
;                     const int t = R - 1 - H2_BSTRIDE * b;
;                     const bool valid = lr >= 1 && lr <= 254 && t >= 0 && t < S;
;                     if (valid) {
;                         u32x2 w;
;                         w.x = pk2(silu_(cvv[m][0][0]) * cvv[m][1][0], silu_(cvv[m][0][1]) * cvv[m][1][1]);
;                         w.y = pk2(silu_(cvv[m][0][2]) * cvv[m][1][2], silu_(cvv[m][0][3]) * cvv[m][1][3]);
;                         *(u32x2*)(act + (size_t)(b * S + t) * DFF + chg) = w;
;                     }
;                 }
.LBB0_1042:
	v_mul_f32_e32 v130, 0xbfb8aa3b, v124
	v_exp_f32_e32 v130, v130
	v_mul_f32_e32 v131, 0xbfb8aa3b, v125
	v_exp_f32_e32 v131, v131
	v_mul_f32_e32 v132, 0xbfb8aa3b, v120
	v_add_f32_e32 v130, 1.0, v130
	v_rcp_f32_e32 v130, v130
	v_add_f32_e32 v131, 1.0, v131
	v_rcp_f32_e32 v131, v131
	v_mul_f32_e32 v124, v124, v130
	v_mul_f32_e32 v124, v126, v124
	v_exp_f32_e32 v126, v132
	v_mul_f32_e32 v130, 0xbfb8aa3b, v121
	v_exp_f32_e32 v130, v130
	v_mul_f32_e32 v125, v125, v131
	v_add_f32_e32 v126, 1.0, v126
	v_mul_f32_e32 v125, v127, v125
	v_rcp_f32_e32 v126, v126
	v_add_f32_e32 v127, 1.0, v130
	v_rcp_f32_e32 v127, v127
	v_cvt_pk_bf16_f32 v250, v124, v125
	v_mul_f32_e32 v120, v120, v126
	v_mul_f32_e32 v120, v122, v120
	v_mul_f32_e32 v121, v121, v127
	v_mul_f32_e32 v121, v123, v121
	v_cvt_pk_bf16_f32 v251, v120, v121
	v_or_b32_e32 v120, v204, v206
	v_mul_lo_u32 v168, v120, s94
	v_lshl_add_u64 v[120:121], s[28:29], 0, v[168:169]
	v_lshl_add_u64 v[120:121], v[246:247], 0, v[120:121]
	v_mov_b32_e32 v248, v230
	v_mov_b32_e32 v249, v231
	s_nop 1
	v_permlane16_swap_b32_e32 v248, v250
	v_permlane16_swap_b32_e32 v249, v251
	global_store_dwordx4 v[120:121], v[248:251], off
	s_or_b64 exec, exec, s[8:9]
	s_and_saveexec_b64 s[8:9], s[50:51]
	s_cbranch_execz .LBB0_1032
.LBB0_1043:
	v_pk_fma_f32 v[122:123], v[52:53], v[80:81], v[88:89]
	v_pk_fma_f32 v[120:121], v[54:55], v[82:83], v[90:91]
	v_pk_fma_f32 v[60:61], v[60:61], v[76:77], v[122:123]
	v_pk_fma_f32 v[62:63], v[62:63], v[78:79], v[120:121]
	v_pk_fma_f32 v[60:61], v[48:49], v[72:73], v[60:61]
	v_pk_fma_f32 v[120:121], v[42:43], v[86:87], v[94:95]
	v_pk_fma_f32 v[122:123], v[40:41], v[84:85], v[92:93]
	v_pk_fma_f32 v[58:59], v[58:59], v[70:71], v[120:121]
	v_mul_f32_e32 v120, 0xbfb8aa3b, v60
	v_exp_f32_e32 v120, v120
	v_mul_f32_e32 v121, 0xbfb8aa3b, v61
	v_exp_f32_e32 v121, v121
	v_pk_fma_f32 v[56:57], v[56:57], v[68:69], v[122:123]
	v_add_f32_e32 v120, 1.0, v120
	v_rcp_f32_e32 v120, v120
	v_add_f32_e32 v121, 1.0, v121
	v_rcp_f32_e32 v121, v121
	v_pk_fma_f32 v[62:63], v[50:51], v[74:75], v[62:63]
	v_pk_fma_f32 v[56:57], v[36:37], v[64:65], v[56:57]
	v_mul_f32_e32 v60, v60, v120
	v_mul_f32_e32 v56, v56, v60
	v_mul_f32_e32 v60, v61, v121
	v_mul_f32_e32 v61, 0xbfb8aa3b, v62
	v_exp_f32_e32 v61, v61
	v_mul_f32_e32 v120, 0xbfb8aa3b, v63
	v_exp_f32_e32 v120, v120
	v_mul_f32_e32 v57, v57, v60
	v_add_f32_e32 v60, 1.0, v61
	v_rcp_f32_e32 v60, v60
	v_add_f32_e32 v61, 1.0, v120
	v_rcp_f32_e32 v61, v61
	v_pk_fma_f32 v[58:59], v[38:39], v[66:67], v[58:59]
	v_cvt_pk_bf16_f32 v254, v56, v57
	v_mul_f32_e32 v57, v62, v60
	v_mul_f32_e32 v57, v58, v57
	v_mul_f32_e32 v58, v63, v61
	v_mul_f32_e32 v58, v59, v58
	v_cvt_pk_bf16_f32 v255, v57, v58
	v_or_b32_e32 v58, v196, v198
	v_mul_lo_u32 v168, v58, s94
	v_lshl_add_u64 v[58:59], s[28:29], 0, v[168:169]
	v_lshl_add_u64 v[58:59], v[246:247], 0, v[58:59]
	v_mov_b32_e32 v252, v232
	v_mov_b32_e32 v253, v233
	s_nop 1
	v_permlane16_swap_b32_e32 v252, v254
	v_permlane16_swap_b32_e32 v253, v255
	global_store_dwordx4 v[58:59], v[252:255], off
	s_or_b64 exec, exec, s[8:9]
	s_and_saveexec_b64 s[8:9], s[52:53]
	s_cbranch_execz .LBB0_1033
.LBB0_1044:
	v_pk_fma_f32 v[48:49], v[48:49], v[80:81], v[88:89]
	v_pk_fma_f32 v[36:37], v[36:37], v[84:85], v[92:93]
	v_pk_fma_f32 v[48:49], v[52:53], v[76:77], v[48:49]
	v_pk_fma_f32 v[36:37], v[40:41], v[68:69], v[36:37]
	v_pk_fma_f32 v[44:45], v[44:45], v[72:73], v[48:49]
	v_pk_fma_f32 v[38:39], v[38:39], v[86:87], v[94:95]
	v_mul_f32_e32 v40, 0xbfb8aa3b, v44
	v_exp_f32_e32 v40, v40
	v_mul_f32_e32 v41, 0xbfb8aa3b, v45
	v_pk_fma_f32 v[38:39], v[42:43], v[70:71], v[38:39]
	v_exp_f32_e32 v41, v41
	v_pk_fma_f32 v[34:35], v[34:35], v[66:67], v[38:39]
	v_add_f32_e32 v38, 1.0, v40
	v_pk_fma_f32 v[50:51], v[50:51], v[82:83], v[90:91]
	v_rcp_f32_e32 v38, v38
	v_pk_fma_f32 v[50:51], v[54:55], v[78:79], v[50:51]
	v_add_f32_e32 v39, 1.0, v41
	v_pk_fma_f32 v[46:47], v[46:47], v[74:75], v[50:51]
	v_rcp_f32_e32 v39, v39
	v_pk_fma_f32 v[32:33], v[32:33], v[64:65], v[36:37]
	v_mul_f32_e32 v37, 0xbfb8aa3b, v46
	v_mul_f32_e32 v36, v44, v38
	v_exp_f32_e32 v37, v37
	v_mul_f32_e32 v38, 0xbfb8aa3b, v47
	v_exp_f32_e32 v38, v38
	v_mul_f32_e32 v32, v32, v36
	v_mul_f32_e32 v36, v45, v39
	v_mul_f32_e32 v33, v33, v36
	v_add_f32_e32 v36, 1.0, v37
	v_rcp_f32_e32 v36, v36
	v_add_f32_e32 v37, 1.0, v38
	v_rcp_f32_e32 v37, v37
	v_cvt_pk_bf16_f32 v250, v32, v33
	v_mul_f32_e32 v33, v46, v36
	v_mul_f32_e32 v33, v34, v33
	v_mul_f32_e32 v34, v47, v37
	v_mul_f32_e32 v34, v35, v34
	v_cvt_pk_bf16_f32 v251, v33, v34
	v_or_b32_e32 v34, v201, v203
	v_mul_lo_u32 v168, v34, s94
	v_lshl_add_u64 v[34:35], s[28:29], 0, v[168:169]
	v_lshl_add_u64 v[34:35], v[246:247], 0, v[34:35]
	v_mov_b32_e32 v248, v234
	v_mov_b32_e32 v249, v235
	s_nop 1
	v_permlane16_swap_b32_e32 v248, v250
	v_permlane16_swap_b32_e32 v249, v251
	global_store_dwordx4 v[34:35], v[248:251], off
	s_or_b64 exec, exec, s[8:9]
	s_and_saveexec_b64 s[8:9], s[54:55]
	s_cbranch_execnz .LBB0_1034
	s_branch .LBB0_1035
; __device__ __forceinline__ unsigned pk2(float lo, float hi) { unsigned r; asm("v_cvt_pk_bf16_f32 %0, %1, %2" : "=v"(r) : "v"(lo), "v"(hi)); return r; }
; __device__ __forceinline__ float silu_(float x) { return x * fast_sigmoid(x); }
;     __device__ __forceinline__ void operator()(const f32x4 (&acc)[2][2][4][2], const Unit& u, int wr, int wc, int fr, int fq) const {
;     ...
; #pragma unroll
;                 for (int m = 0; m < 4; ++m) {
;                     const int lr = 128 * ai + 64 * wr + 4 * fr + m;
;                     const int R = 254 * u.pm + lr;
;                     const int b = R >= (H2_BSTRIDE + 1) ? 1 : 0;
;                     const int t = R - 1 - H2_BSTRIDE * b;
;                     const bool valid = lr >= 1 && lr <= 254 && t >= 0 && t < S;
;                     if (valid) {
;                         u32x2 w;
;                         w.x = pk2(silu_(cvv[m][0][0]) * cvv[m][1][0], silu_(cvv[m][0][1]) * cvv[m][1][1]);
;                         w.y = pk2(silu_(cvv[m][0][2]) * cvv[m][1][2], silu_(cvv[m][0][3]) * cvv[m][1][3]);
;                         *(u32x2*)(act + (size_t)(b * S + t) * DFF + chg) = w;
;                     }
;                 }
.LBB0_1045:
	v_mul_f32_e32 v48, 0xbfb8aa3b, v42
	v_exp_f32_e32 v48, v48
	v_mul_f32_e32 v49, 0xbfb8aa3b, v43
	v_exp_f32_e32 v49, v49
	v_mul_f32_e32 v50, 0xbfb8aa3b, v40
	v_add_f32_e32 v48, 1.0, v48
	v_rcp_f32_e32 v48, v48
	v_add_f32_e32 v49, 1.0, v49
	v_rcp_f32_e32 v49, v49
	v_mul_f32_e32 v42, v42, v48
	v_mul_f32_e32 v42, v46, v42
	v_exp_f32_e32 v46, v50
	v_mul_f32_e32 v48, 0xbfb8aa3b, v41
	v_exp_f32_e32 v48, v48
	v_mul_f32_e32 v43, v43, v49
	v_add_f32_e32 v46, 1.0, v46
	v_mul_f32_e32 v43, v47, v43
	v_rcp_f32_e32 v46, v46
	v_add_f32_e32 v47, 1.0, v48
	v_rcp_f32_e32 v47, v47
	v_cvt_pk_bf16_f32 v254, v42, v43
	v_mul_f32_e32 v40, v40, v46
	v_mul_f32_e32 v40, v44, v40
	v_mul_f32_e32 v41, v41, v47
	v_mul_f32_e32 v41, v45, v41
	v_cvt_pk_bf16_f32 v255, v40, v41
	v_or_b32_e32 v40, v184, v185
	v_mul_lo_u32 v168, v40, s94
	v_lshl_add_u64 v[40:41], s[28:29], 0, v[168:169]
	v_lshl_add_u64 v[40:41], v[246:247], 0, v[40:41]
	v_mov_b32_e32 v252, v238
	v_mov_b32_e32 v253, v239
	s_nop 1
	v_permlane16_swap_b32_e32 v252, v254
	v_permlane16_swap_b32_e32 v253, v255
	global_store_dwordx4 v[40:41], v[252:255], off
	s_or_b64 exec, exec, s[8:9]
	s_and_saveexec_b64 s[8:9], s[58:59]
	s_cbranch_execz .LBB0_1037
.LBB0_1046:
	v_pk_fma_f32 v[42:43], v[20:21], v[80:81], v[88:89]
	v_pk_fma_f32 v[40:41], v[22:23], v[82:83], v[90:91]
	v_pk_fma_f32 v[28:29], v[28:29], v[76:77], v[42:43]
	v_pk_fma_f32 v[30:31], v[30:31], v[78:79], v[40:41]
	v_pk_fma_f32 v[28:29], v[16:17], v[72:73], v[28:29]
	v_pk_fma_f32 v[40:41], v[10:11], v[86:87], v[94:95]
	v_pk_fma_f32 v[42:43], v[8:9], v[84:85], v[92:93]
	v_pk_fma_f32 v[26:27], v[26:27], v[70:71], v[40:41]
	v_mul_f32_e32 v40, 0xbfb8aa3b, v28
	v_exp_f32_e32 v40, v40
	v_mul_f32_e32 v41, 0xbfb8aa3b, v29
	v_exp_f32_e32 v41, v41
	v_pk_fma_f32 v[24:25], v[24:25], v[68:69], v[42:43]
	v_add_f32_e32 v40, 1.0, v40
	v_rcp_f32_e32 v40, v40
	v_add_f32_e32 v41, 1.0, v41
	v_rcp_f32_e32 v41, v41
	v_pk_fma_f32 v[30:31], v[18:19], v[74:75], v[30:31]
	v_pk_fma_f32 v[24:25], v[4:5], v[64:65], v[24:25]
	v_mul_f32_e32 v28, v28, v40
	v_mul_f32_e32 v24, v24, v28
	v_mul_f32_e32 v28, v29, v41
	v_mul_f32_e32 v29, 0xbfb8aa3b, v30
	v_exp_f32_e32 v29, v29
	v_mul_f32_e32 v40, 0xbfb8aa3b, v31
	v_exp_f32_e32 v40, v40
	v_mul_f32_e32 v25, v25, v28
	v_add_f32_e32 v28, 1.0, v29
	v_rcp_f32_e32 v28, v28
	v_add_f32_e32 v29, 1.0, v40
	v_rcp_f32_e32 v29, v29
	v_pk_fma_f32 v[26:27], v[6:7], v[66:67], v[26:27]
	v_cvt_pk_bf16_f32 v250, v24, v25
	v_mul_f32_e32 v25, v30, v28
	v_mul_f32_e32 v25, v26, v25
	v_mul_f32_e32 v26, v31, v29
	v_mul_f32_e32 v26, v27, v26
	v_cvt_pk_bf16_f32 v251, v25, v26
	v_or_b32_e32 v26, v180, v181
	v_mul_lo_u32 v168, v26, s94
	v_lshl_add_u64 v[26:27], s[28:29], 0, v[168:169]
	v_lshl_add_u64 v[26:27], v[246:247], 0, v[26:27]
	v_mov_b32_e32 v248, v240
	v_mov_b32_e32 v249, v241
	s_nop 1
	v_permlane16_swap_b32_e32 v248, v250
	v_permlane16_swap_b32_e32 v249, v251
	global_store_dwordx4 v[26:27], v[248:251], off
	s_or_b64 exec, exec, s[8:9]
	s_and_saveexec_b64 s[8:9], s[60:61]
	s_cbranch_execz .LBB0_1038
.LBB0_1047:
	v_pk_fma_f32 v[16:17], v[16:17], v[80:81], v[88:89]
	v_pk_fma_f32 v[4:5], v[4:5], v[84:85], v[92:93]
	v_pk_fma_f32 v[16:17], v[20:21], v[76:77], v[16:17]
	v_pk_fma_f32 v[4:5], v[8:9], v[68:69], v[4:5]
	v_pk_fma_f32 v[12:13], v[12:13], v[72:73], v[16:17]
	v_pk_fma_f32 v[6:7], v[6:7], v[86:87], v[94:95]
	v_mul_f32_e32 v8, 0xbfb8aa3b, v12
	v_exp_f32_e32 v8, v8
	v_mul_f32_e32 v9, 0xbfb8aa3b, v13
	v_pk_fma_f32 v[6:7], v[10:11], v[70:71], v[6:7]
	v_exp_f32_e32 v9, v9
	v_pk_fma_f32 v[2:3], v[2:3], v[66:67], v[6:7]
	v_add_f32_e32 v6, 1.0, v8
	v_pk_fma_f32 v[18:19], v[18:19], v[82:83], v[90:91]
	v_rcp_f32_e32 v6, v6
	v_pk_fma_f32 v[18:19], v[22:23], v[78:79], v[18:19]
	v_add_f32_e32 v7, 1.0, v9
	v_pk_fma_f32 v[14:15], v[14:15], v[74:75], v[18:19]
	v_rcp_f32_e32 v7, v7
	v_pk_fma_f32 v[0:1], v[0:1], v[64:65], v[4:5]
	v_mul_f32_e32 v5, 0xbfb8aa3b, v14
	v_mul_f32_e32 v4, v12, v6
	v_exp_f32_e32 v5, v5
	v_mul_f32_e32 v6, 0xbfb8aa3b, v15
	v_exp_f32_e32 v6, v6
	v_mul_f32_e32 v0, v0, v4
	v_mul_f32_e32 v4, v13, v7
	v_mul_f32_e32 v1, v1, v4
	v_add_f32_e32 v4, 1.0, v5
	v_rcp_f32_e32 v4, v4
	v_add_f32_e32 v5, 1.0, v6
	v_rcp_f32_e32 v5, v5
	v_cvt_pk_bf16_f32 v254, v0, v1
	v_mul_f32_e32 v1, v14, v4
	v_mul_f32_e32 v1, v2, v1
	v_mul_f32_e32 v2, v15, v5
	v_mul_f32_e32 v2, v3, v2
	v_cvt_pk_bf16_f32 v255, v1, v2
	v_or_b32_e32 v2, v182, v183
	v_mul_lo_u32 v168, v2, s94
	v_lshl_add_u64 v[2:3], s[28:29], 0, v[168:169]
	v_lshl_add_u64 v[2:3], v[246:247], 0, v[2:3]
	v_mov_b32_e32 v252, v242
	v_mov_b32_e32 v253, v243
	s_nop 1
	v_permlane16_swap_b32_e32 v252, v254
	v_permlane16_swap_b32_e32 v253, v255
	global_store_dwordx4 v[2:3], v[252:255], off
	s_or_b64 exec, exec, s[8:9]
	s_and_saveexec_b64 s[8:9], s[14:15]
	s_cbranch_execnz .LBB0_1039
	s_branch .LBB0_1040
